# same as previous best plus: softmax row-max chain reordered so the first VALU read of the last QK MFMA result sits 12 wait states behind it (hazard distance restored for waves 4-7)
# baseline (speedup 1.0000x reference)
; __device__ __forceinline__ float max3f(float a, float b, float c) { float r; asm("v_max3_f32 %0, %1, %2, %3" : "=v"(r) : "v"(a), "v"(b), "v"(c)); return r; }
; __device__ __forceinline__ void attn_phase(KA a, lds8* lds, int tid, int lane, int wave) {
;     ...
;             for (int r = 0; r < 16; ++r) { s0[r] = __builtin_amdgcn_exp2f(s0[r]); s1[r] = __builtin_amdgcn_exp2f(s1[r]); }
;             float mx = max3f(s0[0], s1[0], s0[1]);
;             mx = max3f(mx, s1[1], s0[2]); mx = max3f(mx, s1[2], s0[3]); mx = max3f(mx, s1[3], s0[4]); mx = max3f(mx, s1[4], s0[5]); mx = max3f(mx, s1[5], s0[6]); mx = max3f(mx, s1[6], s0[7]); mx = max3f(mx, s1[7], s0[8]);
;             mx = max3f(mx, s1[8], s0[9]); mx = max3f(mx, s1[9], s0[10]); mx = max3f(mx, s1[10], s0[11]); mx = max3f(mx, s1[11], s0[12]); mx = max3f(mx, s1[12], s0[13]); mx = max3f(mx, s1[13], s0[14]); mx = max3f(mx, s1[14], s0[15]);
;             mx = fmaxf(mx, s1[15]);
;             mx = fmaxf(mx, __shfl_xor(mx, 32));
;             const bool mv = (mx > 256.0f) | (mx < 0.00390625f);
;             if (__any(mv)) { const float al = mv ? __builtin_amdgcn_rcpf(mx) : 1.0f; const float dl = mv ? __builtin_amdgcn_logf(mx) : 0.f;
;                 lsA *= al; lsB *= al; lsC *= al; lsD *= al;
; #pragma unroll
;                 for (int db = 0; db < 4; ++db) O[db] = O[db] * al;
;                 negm = negm - dl; s0 = s0 * al; s1 = s1 * al; }
.LBB0_1310:
	s_nop 9
	v_max3_f32 v235, v96, v97, v98
	v_max3_f32 v235, v235, v80, v81
	v_max3_f32 v235, v235, v82, v83
	v_max3_f32 v235, v235, v84, v85
	v_max3_f32 v235, v235, v86, v87
	v_max3_f32 v235, v235, v88, v89
	v_max3_f32 v235, v235, v90, v91
	v_max3_f32 v235, v235, v92, v93
	v_max3_f32 v235, v235, v94, v95
	v_max3_f32 v235, v235, v99, v100
	v_max3_f32 v235, v235, v101, v102
	v_max3_f32 v235, v235, v103, v104
	v_max3_f32 v235, v235, v105, v106
	v_max3_f32 v235, v235, v107, v108
	v_max3_f32 v235, v235, v109, v110
	v_max_f32_e32 v235, v235, v111
	v_xor_b32_e32 v251, 32, v248
	v_lshlrev_b32_e32 v251, 2, v251
	ds_bpermute_b32 v249, v251, v235
	v_exp_f32_e32 v224, v96
	v_exp_f32_e32 v80, v80
	v_exp_f32_e32 v225, v97
	v_exp_f32_e32 v220, v84
	v_exp_f32_e32 v84, v88
	v_exp_f32_e32 v81, v81
	v_exp_f32_e32 v226, v98
	v_exp_f32_e32 v82, v82
	v_exp_f32_e32 v227, v99
	v_exp_f32_e32 v83, v83
	v_exp_f32_e32 v228, v100
	v_exp_f32_e32 v229, v101
	v_exp_f32_e32 v221, v85
	v_exp_f32_e32 v230, v102
	v_exp_f32_e32 v222, v86
	v_exp_f32_e32 v231, v103
	v_exp_f32_e32 v223, v87
	v_exp_f32_e32 v100, v104
	v_exp_f32_e32 v101, v105
	v_exp_f32_e32 v85, v89
	v_exp_f32_e32 v102, v106
	v_exp_f32_e32 v86, v90
	v_exp_f32_e32 v103, v107
	v_exp_f32_e32 v87, v91
	v_exp_f32_e32 v104, v108
	v_mov_b32_e32 v108, v251
	v_exp_f32_e32 v98, v92
	v_exp_f32_e32 v105, v109
	v_exp_f32_e32 v97, v95
	v_exp_f32_e32 v99, v93
	v_exp_f32_e32 v106, v110
	v_exp_f32_e32 v96, v94
	v_exp_f32_e32 v107, v111
	s_waitcnt lgkmcnt(0)
	v_max_f32_e32 v235, v235, v249
	v_exp_f32_e32 v88, v235
	s_nop 0
	v_cmp_lt_f32_e32 vcc, s40, v88
	v_cmp_gt_f32_e64 s[14:15], s41, v88
	s_or_b64 vcc, vcc, s[14:15]
	s_cbranch_vccz .LBB0_1312
	v_rcp_f32_e32 v89, v88
	v_log_f32_e32 v90, v88
	v_cndmask_b32_e32 v88, 1.0, v89, vcc
	v_pk_mul_f32 v[62:63], v[62:63], v[88:89] op_sel_hi:[1,0]
	v_pk_mul_f32 v[60:61], v[60:61], v[88:89] op_sel_hi:[1,0]
	v_pk_mul_f32 v[58:59], v[58:59], v[88:89] op_sel_hi:[1,0]
	v_pk_mul_f32 v[56:57], v[56:57], v[88:89] op_sel_hi:[1,0]
	v_pk_mul_f32 v[54:55], v[54:55], v[88:89] op_sel_hi:[1,0]
	v_pk_mul_f32 v[52:53], v[52:53], v[88:89] op_sel_hi:[1,0]
	v_pk_mul_f32 v[50:51], v[50:51], v[88:89] op_sel_hi:[1,0]
	v_pk_mul_f32 v[48:49], v[48:49], v[88:89] op_sel_hi:[1,0]
	v_pk_mul_f32 v[46:47], v[46:47], v[88:89] op_sel_hi:[1,0]
	v_pk_mul_f32 v[44:45], v[44:45], v[88:89] op_sel_hi:[1,0]
	v_pk_mul_f32 v[42:43], v[42:43], v[88:89] op_sel_hi:[1,0]
	v_pk_mul_f32 v[40:41], v[40:41], v[88:89] op_sel_hi:[1,0]
	v_pk_mul_f32 v[38:39], v[38:39], v[88:89] op_sel_hi:[1,0]
	v_pk_mul_f32 v[36:37], v[36:37], v[88:89] op_sel_hi:[1,0]
	v_pk_mul_f32 v[34:35], v[34:35], v[88:89] op_sel_hi:[1,0]
	v_pk_mul_f32 v[32:33], v[32:33], v[88:89] op_sel_hi:[1,0]
	v_pk_mul_f32 v[30:31], v[30:31], v[88:89] op_sel_hi:[1,0]
	v_pk_mul_f32 v[28:29], v[28:29], v[88:89] op_sel_hi:[1,0]
	v_pk_mul_f32 v[26:27], v[26:27], v[88:89] op_sel_hi:[1,0]
	v_pk_mul_f32 v[24:25], v[24:25], v[88:89] op_sel_hi:[1,0]
	v_pk_mul_f32 v[22:23], v[22:23], v[88:89] op_sel_hi:[1,0]
	v_pk_mul_f32 v[20:21], v[20:21], v[88:89] op_sel_hi:[1,0]
	v_pk_mul_f32 v[18:19], v[18:19], v[88:89] op_sel_hi:[1,0]
	v_pk_mul_f32 v[16:17], v[16:17], v[88:89] op_sel_hi:[1,0]
	v_pk_mul_f32 v[14:15], v[14:15], v[88:89] op_sel_hi:[1,0]
	v_pk_mul_f32 v[12:13], v[12:13], v[88:89] op_sel_hi:[1,0]
	v_pk_mul_f32 v[10:11], v[10:11], v[88:89] op_sel_hi:[1,0]
	v_pk_mul_f32 v[8:9], v[8:9], v[88:89] op_sel_hi:[1,0]
	v_pk_mul_f32 v[6:7], v[6:7], v[88:89] op_sel_hi:[1,0]
	v_pk_mul_f32 v[4:5], v[4:5], v[88:89] op_sel_hi:[1,0]
	v_pk_mul_f32 v[2:3], v[2:3], v[88:89] op_sel_hi:[1,0]
	v_pk_mul_f32 v[0:1], v[0:1], v[88:89] op_sel_hi:[1,0]
	v_cndmask_b32_e32 v89, 0, v90, vcc
	v_pk_mul_f32 v[210:211], v[210:211], v[88:89] op_sel_hi:[1,0]
	v_pk_mul_f32 v[208:209], v[208:209], v[88:89] op_sel_hi:[1,0]
	v_sub_f32_e32 v79, v79, v89
	v_sub_f32_e32 v78, v78, v89
	v_sub_f32_e32 v77, v77, v89
	v_sub_f32_e32 v76, v76, v89
	v_sub_f32_e32 v75, v75, v89
	v_sub_f32_e32 v74, v74, v89
	v_sub_f32_e32 v73, v73, v89
	v_sub_f32_e32 v72, v72, v89
	v_sub_f32_e32 v71, v71, v89
	v_sub_f32_e32 v70, v70, v89
	v_sub_f32_e32 v69, v69, v89
	v_sub_f32_e32 v68, v68, v89
	v_sub_f32_e32 v67, v67, v89
	v_sub_f32_e32 v66, v66, v89
	v_sub_f32_e32 v65, v65, v89
	v_sub_f32_e32 v64, v64, v89
	v_pk_mul_f32 v[106:107], v[106:107], v[88:89] op_sel_hi:[1,0]
	v_pk_mul_f32 v[104:105], v[104:105], v[88:89] op_sel_hi:[1,0]
	v_pk_mul_f32 v[102:103], v[102:103], v[88:89] op_sel_hi:[1,0]
	v_pk_mul_f32 v[100:101], v[100:101], v[88:89] op_sel_hi:[1,0]
	v_pk_mul_f32 v[230:231], v[230:231], v[88:89] op_sel_hi:[1,0]
	v_pk_mul_f32 v[228:229], v[228:229], v[88:89] op_sel_hi:[1,0]
	v_pk_mul_f32 v[226:227], v[226:227], v[88:89] op_sel_hi:[1,0]
	v_pk_mul_f32 v[224:225], v[224:225], v[88:89] op_sel_hi:[1,0]
	v_pk_mul_f32 v[96:97], v[96:97], v[88:89] op_sel_hi:[1,0]
	v_pk_mul_f32 v[98:99], v[98:99], v[88:89] op_sel_hi:[1,0]
	v_pk_mul_f32 v[86:87], v[86:87], v[88:89] op_sel_hi:[1,0]
	v_pk_mul_f32 v[84:85], v[84:85], v[88:89] op_sel_hi:[1,0]
	v_pk_mul_f32 v[222:223], v[222:223], v[88:89] op_sel_hi:[1,0]
	v_pk_mul_f32 v[220:221], v[220:221], v[88:89] op_sel_hi:[1,0]
	v_pk_mul_f32 v[82:83], v[82:83], v[88:89] op_sel_hi:[1,0]
	v_pk_mul_f32 v[80:81], v[80:81], v[88:89] op_sel_hi:[1,0]
